# P4 prompt attention: sinks[hq] fetched with a scalar load (wave-uniform) so its wait no longer drains the 20 K/V/Q prefetch loads issued just before
# speedup vs baseline: 1.0213x; 1.0030x over previous
; #define LAS __attribute__((address_space(3)))
; __device__ __forceinline__ void phase_attention(KParams P, LAS unsigned char* lds, const int wave_sg) {
;     ...
;         const float sd = exp2f(-0.4f * (float)(hq + 1)) * LOG2E * (float)dil;
;         __syncthreads();
; #pragma unroll
;         for (int c = 0; c < 8; ++c) { const int ch = htid + 256 * c, row = ch >> 3, cc = ch & 7; *(LAS u32x4*)(Kl + row * ATT_KROW + cc * 16) = kreg[c]; *(LAS u32x4*)(Vl + row * ATT_KROW + cc * 16) = vreg[c]; }
;         bf16x8 qf[4];
; #pragma unroll
;         for (int d0 = 0; d0 < 4; ++d0) qf[d0] = qn[d0];
;         __syncthreads();
;         if (pair + (int)gridDim.x < 2560) ATT_LOAD(pair + (int)gridDim.x);
;         float sink2 = 0.f, mx = -1e30f, lsum = 0.f;
;         if (hq < 8) { sink2 = sinks[hq] * LOG2E; mx = sink2; lsum = hi == 0 ? 1.f : 0.f; }
.LBB0_812:
	v_mov_b32_e32 v1, 0x42800000
	v_cndmask_b32_e64 v1, 0, v1, s[76:77]
	v_fmac_f32_e32 v1, 0xbecccccd, v0
	v_exp_f32_e32 v0, v1
	s_cmp_lt_i32 s82, 8
	s_cselect_b64 s[0:1], -1, 0
	s_cmp_gt_i32 s82, 7
	s_cselect_b64 s[76:77], -1, 0
	v_ldexp_f32 v0, v0, s81
	s_and_b64 vcc, exec, s[76:77]
	s_cbranch_vccnz .LBB0_814
	s_ashr_i32 s83, s82, 31
	s_lshl_b64 s[94:95], s[82:83], 2
	s_add_u32 s94, s92, s94
	s_addc_u32 s95, s93, s95
	s_load_dword s94, s[94:95], 0x0
	v_cndmask_b32_e64 v32, 0, 1.0, s[8:9]
	s_waitcnt lgkmcnt(0)
	v_mov_b32_e32 v1, s94
	v_mul_f32_e32 v16, 0x3fb8aa3b, v1
	s_branch .LBB0_815
